# GEMM1 epilogue output stores marked nt (streaming) to keep A/B panel lines in L2
# baseline (speedup 1.0000x reference)
.LBB0_323:
	s_add_i32 s5, s29, s46
	s_and_b32 s0, s34, -4
	s_cmp_eq_u32 s0, 8
	s_cselect_b64 s[0:1], -1, 0
	s_cmp_lt_i32 s44, 32
	s_cselect_b64 s[16:17], -1, 0
	v_or_b32_e32 v150, s5, v1
	v_mov_b64_e32 v[146:147], s[94:95]
	s_and_b64 s[16:17], s[0:1], s[16:17]
	s_ashr_i32 s4, s5, 7
	v_mad_i64_i32 v[146:147], s[50:51], v150, s20, v[146:147]
	v_ashrrev_i32_e32 v145, 31, v144
	v_cndmask_b32_e64 v149, 0, 1, s[16:17]
	s_and_b32 s4, s4, -2
	v_bitop3_b32 v148, s5, v237, v1 bitop3:0xc8
	v_lshl_add_u64 v[146:147], v[144:145], 1, v[146:147]
	v_cmp_ne_u32_e64 s[0:1], 1, v149
	s_andn2_b64 vcc, exec, s[16:17]
	v_cvt_pk_bf16_f32 v152, v126, v127
	v_cvt_pk_bf16_f32 v153, v128, v129
	v_cvt_pk_bf16_f32 v154, v122, v123
	v_cvt_pk_bf16_f32 v155, v124, v125
	global_store_dwordx4 v[146:147], v[152:155], off nt
	s_cbranch_vccnz .LBB0_325
	s_or_b32 s5, s4, s97
	v_lshl_or_b32 v152, s5, 8, v148
	v_ashrrev_i32_e32 v153, 31, v152
	v_lshlrev_b64 v[152:153], 12, v[152:153]
	v_lshl_add_u64 v[152:153], s[84:85], 0, v[152:153]
	v_lshl_add_u64 v[152:153], v[144:145], 2, v[152:153]
	v_add_co_u32_e32 v154, vcc, 0xffffe000, v152
	s_nop 1
	v_addc_co_u32_e32 v155, vcc, -1, v153, vcc
	v_add_co_u32_e32 v152, vcc, 0xfffff000, v152
	global_store_dwordx4 v[154:155], v[126:129], off nt
	s_nop 0
	v_addc_co_u32_e32 v153, vcc, -1, v153, vcc
	global_store_dwordx4 v[152:153], v[122:125], off offset:-4080 nt
.LBB0_325:
	s_and_b64 vcc, exec, s[0:1]
	v_cvt_pk_bf16_f32 v152, v118, v119
	v_cvt_pk_bf16_f32 v153, v120, v121
	v_cvt_pk_bf16_f32 v154, v110, v111
	v_cvt_pk_bf16_f32 v155, v112, v113
	global_store_dwordx4 v[146:147], v[152:155], off offset:256 nt
	s_cbranch_vccnz .LBB0_327
	s_or_b32 s5, s4, s97
	v_lshl_or_b32 v146, s5, 8, v148
	v_ashrrev_i32_e32 v147, 31, v146
	v_lshlrev_b64 v[146:147], 12, v[146:147]
	v_lshl_add_u64 v[146:147], s[84:85], 0, v[146:147]
	v_lshl_add_u64 v[146:147], v[144:145], 2, v[146:147]
	v_add_co_u32_e32 v146, vcc, 0xfffff000, v146
	s_nop 1
	v_addc_co_u32_e32 v147, vcc, -1, v147, vcc
	global_store_dwordx4 v[146:147], v[118:121], off offset:-3584 nt
	global_store_dwordx4 v[146:147], v[110:113], off offset:-3568 nt
.LBB0_327:
	v_or_b32_e32 v149, 16, v150
	v_mov_b64_e32 v[146:147], s[94:95]
	s_movk_i32 s5, 0xdf
	v_mad_i64_i32 v[146:147], s[16:17], v149, s20, v[146:147]
	v_bitop3_b32 v148, v150, s5, 16 bitop3:0xc8
	v_lshl_add_u64 v[146:147], v[144:145], 1, v[146:147]
	s_and_b64 vcc, exec, s[0:1]
	v_cvt_pk_bf16_f32 v152, v114, v115
	v_cvt_pk_bf16_f32 v153, v116, v117
	v_cvt_pk_bf16_f32 v154, v106, v107
	v_cvt_pk_bf16_f32 v155, v108, v109
	global_store_dwordx4 v[146:147], v[152:155], off nt
	s_cbranch_vccnz .LBB0_329
	s_or_b32 s5, s4, s97
	v_lshl_or_b32 v152, s5, 8, v148
	v_ashrrev_i32_e32 v153, 31, v152
	v_lshlrev_b64 v[152:153], 12, v[152:153]
	v_lshl_add_u64 v[152:153], s[84:85], 0, v[152:153]
	v_lshl_add_u64 v[152:153], v[144:145], 2, v[152:153]
	v_add_co_u32_e32 v154, vcc, 0xffffe000, v152
	s_nop 1
	v_addc_co_u32_e32 v155, vcc, -1, v153, vcc
	v_add_co_u32_e32 v152, vcc, 0xfffff000, v152
	global_store_dwordx4 v[154:155], v[114:117], off nt
	s_nop 0
	v_addc_co_u32_e32 v153, vcc, -1, v153, vcc
	global_store_dwordx4 v[152:153], v[106:109], off offset:-4080 nt
.LBB0_329:
	s_and_b64 vcc, exec, s[0:1]
	v_cvt_pk_bf16_f32 v152, v98, v99
	v_cvt_pk_bf16_f32 v153, v100, v101
	v_cvt_pk_bf16_f32 v154, v90, v91
	v_cvt_pk_bf16_f32 v155, v92, v93
	global_store_dwordx4 v[146:147], v[152:155], off offset:256 nt
	s_cbranch_vccnz .LBB0_331
	s_or_b32 s5, s4, s97
	v_lshl_or_b32 v146, s5, 8, v148
	v_ashrrev_i32_e32 v147, 31, v146
	v_lshlrev_b64 v[146:147], 12, v[146:147]
	v_lshl_add_u64 v[146:147], s[84:85], 0, v[146:147]
	v_lshl_add_u64 v[146:147], v[144:145], 2, v[146:147]
	v_add_co_u32_e32 v146, vcc, 0xfffff000, v146
	s_nop 1
	v_addc_co_u32_e32 v147, vcc, -1, v147, vcc
	global_store_dwordx4 v[146:147], v[98:101], off offset:-3584 nt
	global_store_dwordx4 v[146:147], v[90:93], off offset:-3568 nt
.LBB0_331:
	v_or_b32_e32 v149, 32, v150
	v_mov_b64_e32 v[146:147], s[94:95]
	s_movk_i32 s5, 0xef
	v_mad_i64_i32 v[146:147], s[16:17], v149, s20, v[146:147]
	v_bitop3_b32 v148, v150, s5, 32 bitop3:0xc8
	v_lshl_add_u64 v[146:147], v[144:145], 1, v[146:147]
	s_and_b64 vcc, exec, s[0:1]
	v_cvt_pk_bf16_f32 v152, v102, v103
	v_cvt_pk_bf16_f32 v153, v104, v105
	v_cvt_pk_bf16_f32 v154, v94, v95
	v_cvt_pk_bf16_f32 v155, v96, v97
	global_store_dwordx4 v[146:147], v[152:155], off nt
	s_cbranch_vccnz .LBB0_333
	s_or_b32 s5, s4, s97
	v_lshl_or_b32 v152, s5, 8, v148
	v_ashrrev_i32_e32 v153, 31, v152
	v_lshlrev_b64 v[152:153], 12, v[152:153]
	v_lshl_add_u64 v[152:153], s[84:85], 0, v[152:153]
	v_lshl_add_u64 v[152:153], v[144:145], 2, v[152:153]
	v_add_co_u32_e32 v154, vcc, 0xffffe000, v152
	s_nop 1
	v_addc_co_u32_e32 v155, vcc, -1, v153, vcc
	v_add_co_u32_e32 v152, vcc, 0xfffff000, v152
	global_store_dwordx4 v[154:155], v[102:105], off nt
	s_nop 0
	v_addc_co_u32_e32 v153, vcc, -1, v153, vcc
	global_store_dwordx4 v[152:153], v[94:97], off offset:-4080 nt
.LBB0_333:
	s_and_b64 vcc, exec, s[0:1]
	v_cvt_pk_bf16_f32 v152, v82, v83
	v_cvt_pk_bf16_f32 v153, v84, v85
	v_cvt_pk_bf16_f32 v154, v74, v75
	v_cvt_pk_bf16_f32 v155, v76, v77
	global_store_dwordx4 v[146:147], v[152:155], off offset:256 nt
	s_cbranch_vccnz .LBB0_335
	s_or_b32 s5, s4, s97
	v_lshl_or_b32 v146, s5, 8, v148
	v_ashrrev_i32_e32 v147, 31, v146
	v_lshlrev_b64 v[146:147], 12, v[146:147]
	v_lshl_add_u64 v[146:147], s[84:85], 0, v[146:147]
	v_lshl_add_u64 v[146:147], v[144:145], 2, v[146:147]
	v_add_co_u32_e32 v146, vcc, 0xfffff000, v146
	s_nop 1
	v_addc_co_u32_e32 v147, vcc, -1, v147, vcc
	global_store_dwordx4 v[146:147], v[82:85], off offset:-3584 nt
	global_store_dwordx4 v[146:147], v[74:77], off offset:-3568 nt
.LBB0_335:
	v_or_b32_e32 v149, 48, v150
	v_mov_b64_e32 v[146:147], s[94:95]
	s_movk_i32 s5, 0xff
	v_mad_i64_i32 v[146:147], s[16:17], v149, s20, v[146:147]
	v_bitop3_b32 v148, v150, s5, 48 bitop3:0xc8
	v_lshl_add_u64 v[146:147], v[144:145], 1, v[146:147]
	s_and_b64 vcc, exec, s[0:1]
	v_cvt_pk_bf16_f32 v152, v86, v87
	v_cvt_pk_bf16_f32 v153, v88, v89
	v_cvt_pk_bf16_f32 v154, v78, v79
	v_cvt_pk_bf16_f32 v155, v80, v81
	global_store_dwordx4 v[146:147], v[152:155], off nt
	s_cbranch_vccnz .LBB0_337
	s_or_b32 s5, s4, s97
	v_lshl_or_b32 v152, s5, 8, v148
	v_ashrrev_i32_e32 v153, 31, v152
	v_lshlrev_b64 v[152:153], 12, v[152:153]
	v_lshl_add_u64 v[152:153], s[84:85], 0, v[152:153]
	v_lshl_add_u64 v[152:153], v[144:145], 2, v[152:153]
	v_add_co_u32_e32 v154, vcc, 0xffffe000, v152
	s_nop 1
	v_addc_co_u32_e32 v155, vcc, -1, v153, vcc
	v_add_co_u32_e32 v152, vcc, 0xfffff000, v152
	global_store_dwordx4 v[154:155], v[86:89], off nt
	s_nop 0
	v_addc_co_u32_e32 v153, vcc, -1, v153, vcc
	global_store_dwordx4 v[152:153], v[78:81], off offset:-4080 nt
.LBB0_337:
	s_and_b64 vcc, exec, s[0:1]
	v_cvt_pk_bf16_f32 v152, v70, v71
	v_cvt_pk_bf16_f32 v153, v72, v73
	v_cvt_pk_bf16_f32 v154, v66, v67
	v_cvt_pk_bf16_f32 v155, v68, v69
	global_store_dwordx4 v[146:147], v[152:155], off offset:256 nt
	s_cbranch_vccnz .LBB0_339
	s_or_b32 s4, s4, s97
	v_lshl_or_b32 v146, s4, 8, v148
	v_ashrrev_i32_e32 v147, 31, v146
	v_lshlrev_b64 v[146:147], 12, v[146:147]
	v_lshl_add_u64 v[146:147], s[84:85], 0, v[146:147]
	v_lshl_add_u64 v[146:147], v[144:145], 2, v[146:147]
	v_add_co_u32_e32 v146, vcc, 0xfffff000, v146
	s_nop 1
	v_addc_co_u32_e32 v147, vcc, -1, v147, vcc
	global_store_dwordx4 v[146:147], v[70:73], off offset:-3584 nt
	global_store_dwordx4 v[146:147], v[66:69], off offset:-3568 nt
.LBB0_339:
	v_add_u32_e32 v148, 0x80, v150
	v_ashrrev_i32_e32 v146, 7, v148
	v_and_b32_e32 v151, -2, v146
	v_mov_b64_e32 v[146:147], s[94:95]
	v_and_b32_e32 v156, 0xcf, v148
	v_mad_i64_i32 v[146:147], s[4:5], v148, s20, v[146:147]
	v_or_b32_e32 v151, s97, v151
	v_lshl_add_u64 v[148:149], v[144:145], 1, v[146:147]
	s_and_b64 vcc, exec, s[0:1]
	v_lshl_or_b32 v146, v151, 8, v156
	v_cvt_pk_bf16_f32 v152, v62, v63
	v_cvt_pk_bf16_f32 v153, v64, v65
	v_cvt_pk_bf16_f32 v154, v58, v59
	v_cvt_pk_bf16_f32 v155, v60, v61
	global_store_dwordx4 v[148:149], v[152:155], off nt
	s_cbranch_vccnz .LBB0_341
	v_ashrrev_i32_e32 v147, 31, v146
	v_lshlrev_b64 v[152:153], 12, v[146:147]
	v_lshl_add_u64 v[152:153], s[84:85], 0, v[152:153]
	v_lshl_add_u64 v[152:153], v[144:145], 2, v[152:153]
	v_add_co_u32_e32 v154, vcc, 0xffffe000, v152
	s_nop 1
	v_addc_co_u32_e32 v155, vcc, -1, v153, vcc
	v_add_co_u32_e32 v152, vcc, 0xfffff000, v152
	global_store_dwordx4 v[154:155], v[62:65], off nt
	s_nop 0
	v_addc_co_u32_e32 v153, vcc, -1, v153, vcc
	global_store_dwordx4 v[152:153], v[58:61], off offset:-4080 nt
.LBB0_341:
	s_and_b64 vcc, exec, s[0:1]
	v_cvt_pk_bf16_f32 v152, v50, v51
	v_cvt_pk_bf16_f32 v153, v52, v53
	v_cvt_pk_bf16_f32 v154, v42, v43
	v_cvt_pk_bf16_f32 v155, v44, v45
	global_store_dwordx4 v[148:149], v[152:155], off offset:256 nt
	s_cbranch_vccnz .LBB0_343
	v_ashrrev_i32_e32 v147, 31, v146
	v_lshlrev_b64 v[146:147], 12, v[146:147]
	v_lshl_add_u64 v[146:147], s[84:85], 0, v[146:147]
	v_lshl_add_u64 v[146:147], v[144:145], 2, v[146:147]
	v_add_co_u32_e32 v146, vcc, 0xfffff000, v146
	s_nop 1
	v_addc_co_u32_e32 v147, vcc, -1, v147, vcc
	global_store_dwordx4 v[146:147], v[50:53], off offset:-3584 nt
	global_store_dwordx4 v[146:147], v[42:45], off offset:-3568 nt
.LBB0_343:
	v_add_u32_e32 v148, 0x90, v150
	v_mov_b64_e32 v[146:147], s[94:95]
	v_and_b32_e32 v156, 0xdf, v148
	v_mad_i64_i32 v[146:147], s[4:5], v148, s20, v[146:147]
	v_lshl_add_u64 v[148:149], v[144:145], 1, v[146:147]
	s_and_b64 vcc, exec, s[0:1]
	v_lshl_or_b32 v146, v151, 8, v156
	v_cvt_pk_bf16_f32 v152, v54, v55
	v_cvt_pk_bf16_f32 v153, v56, v57
	v_cvt_pk_bf16_f32 v154, v46, v47
	v_cvt_pk_bf16_f32 v155, v48, v49
	global_store_dwordx4 v[148:149], v[152:155], off nt
	s_cbranch_vccnz .LBB0_345
	v_ashrrev_i32_e32 v147, 31, v146
	v_lshlrev_b64 v[152:153], 12, v[146:147]
	v_lshl_add_u64 v[152:153], s[84:85], 0, v[152:153]
	v_lshl_add_u64 v[152:153], v[144:145], 2, v[152:153]
	v_add_co_u32_e32 v154, vcc, 0xffffe000, v152
	s_nop 1
	v_addc_co_u32_e32 v155, vcc, -1, v153, vcc
	v_add_co_u32_e32 v152, vcc, 0xfffff000, v152
	global_store_dwordx4 v[154:155], v[54:57], off nt
	s_nop 0
	v_addc_co_u32_e32 v153, vcc, -1, v153, vcc
	global_store_dwordx4 v[152:153], v[46:49], off offset:-4080 nt
.LBB0_345:
	s_and_b64 vcc, exec, s[0:1]
	v_cvt_pk_bf16_f32 v152, v34, v35
	v_cvt_pk_bf16_f32 v153, v36, v37
	v_cvt_pk_bf16_f32 v154, v26, v27
	v_cvt_pk_bf16_f32 v155, v28, v29
	global_store_dwordx4 v[148:149], v[152:155], off offset:256 nt
	s_cbranch_vccnz .LBB0_347
	v_ashrrev_i32_e32 v147, 31, v146
	v_lshlrev_b64 v[146:147], 12, v[146:147]
	v_lshl_add_u64 v[146:147], s[84:85], 0, v[146:147]
	v_lshl_add_u64 v[146:147], v[144:145], 2, v[146:147]
	v_add_co_u32_e32 v146, vcc, 0xfffff000, v146
	s_nop 1
	v_addc_co_u32_e32 v147, vcc, -1, v147, vcc
	global_store_dwordx4 v[146:147], v[34:37], off offset:-3584 nt
	global_store_dwordx4 v[146:147], v[26:29], off offset:-3568 nt
.LBB0_347:
	v_add_u32_e32 v148, 0xa0, v150
	v_mov_b64_e32 v[146:147], s[94:95]
	v_and_b32_e32 v156, 0xef, v148
	v_mad_i64_i32 v[146:147], s[4:5], v148, s20, v[146:147]
	v_lshl_add_u64 v[148:149], v[144:145], 1, v[146:147]
	s_and_b64 vcc, exec, s[0:1]
	v_lshl_or_b32 v146, v151, 8, v156
	v_cvt_pk_bf16_f32 v152, v38, v39
	v_cvt_pk_bf16_f32 v153, v40, v41
	v_cvt_pk_bf16_f32 v154, v30, v31
	v_cvt_pk_bf16_f32 v155, v32, v33
	global_store_dwordx4 v[148:149], v[152:155], off nt
	s_cbranch_vccnz .LBB0_349
	v_ashrrev_i32_e32 v147, 31, v146
	v_lshlrev_b64 v[152:153], 12, v[146:147]
	v_lshl_add_u64 v[152:153], s[84:85], 0, v[152:153]
	v_lshl_add_u64 v[152:153], v[144:145], 2, v[152:153]
	v_add_co_u32_e32 v154, vcc, 0xffffe000, v152
	s_nop 1
	v_addc_co_u32_e32 v155, vcc, -1, v153, vcc
	v_add_co_u32_e32 v152, vcc, 0xfffff000, v152
	global_store_dwordx4 v[154:155], v[38:41], off nt
	s_nop 0
	v_addc_co_u32_e32 v153, vcc, -1, v153, vcc
	global_store_dwordx4 v[152:153], v[30:33], off offset:-4080 nt
.LBB0_349:
	s_and_b64 vcc, exec, s[0:1]
	v_cvt_pk_bf16_f32 v152, v18, v19
	v_cvt_pk_bf16_f32 v153, v20, v21
	v_cvt_pk_bf16_f32 v154, v10, v11
	v_cvt_pk_bf16_f32 v155, v12, v13
	global_store_dwordx4 v[148:149], v[152:155], off offset:256 nt
	s_cbranch_vccnz .LBB0_351
	v_ashrrev_i32_e32 v147, 31, v146
	v_lshlrev_b64 v[146:147], 12, v[146:147]
	v_lshl_add_u64 v[146:147], s[84:85], 0, v[146:147]
	v_lshl_add_u64 v[146:147], v[144:145], 2, v[146:147]
	v_add_co_u32_e32 v146, vcc, 0xfffff000, v146
	s_nop 1
	v_addc_co_u32_e32 v147, vcc, -1, v147, vcc
	global_store_dwordx4 v[146:147], v[18:21], off offset:-3584 nt
	global_store_dwordx4 v[146:147], v[10:13], off offset:-3568 nt
.LBB0_351:
	v_add_u32_e32 v148, 0xb0, v150
	v_mov_b64_e32 v[146:147], s[94:95]
	v_and_b32_e32 v150, 0xff, v148
	v_mad_i64_i32 v[146:147], s[4:5], v148, s20, v[146:147]
	v_lshl_add_u64 v[148:149], v[144:145], 1, v[146:147]
	s_and_b64 vcc, exec, s[0:1]
	v_lshl_or_b32 v146, v151, 8, v150
	v_cvt_pk_bf16_f32 v152, v22, v23
	v_cvt_pk_bf16_f32 v153, v24, v25
	v_cvt_pk_bf16_f32 v154, v14, v15
	v_cvt_pk_bf16_f32 v155, v16, v17
	global_store_dwordx4 v[148:149], v[152:155], off nt
	s_cbranch_vccnz .LBB0_353
	v_ashrrev_i32_e32 v147, 31, v146
	v_lshlrev_b64 v[150:151], 12, v[146:147]
	v_lshl_add_u64 v[150:151], s[84:85], 0, v[150:151]
	v_lshl_add_u64 v[150:151], v[144:145], 2, v[150:151]
	v_add_co_u32_e32 v152, vcc, 0xffffe000, v150
	s_nop 1
	v_addc_co_u32_e32 v153, vcc, -1, v151, vcc
	v_add_co_u32_e32 v150, vcc, 0xfffff000, v150
	global_store_dwordx4 v[152:153], v[22:25], off nt
	s_nop 0
	v_addc_co_u32_e32 v151, vcc, -1, v151, vcc
	global_store_dwordx4 v[150:151], v[14:17], off offset:-4080 nt
.LBB0_353:
	s_and_b64 vcc, exec, s[0:1]
	v_cvt_pk_bf16_f32 v150, v6, v7
	v_cvt_pk_bf16_f32 v151, v8, v9
	v_cvt_pk_bf16_f32 v152, v2, v3
	v_cvt_pk_bf16_f32 v153, v4, v5
	global_store_dwordx4 v[148:149], v[150:153], off offset:256 nt
	s_cbranch_vccnz .LBB0_355
	v_ashrrev_i32_e32 v147, 31, v146
	v_lshlrev_b64 v[146:147], 12, v[146:147]
	v_lshl_add_u64 v[146:147], s[84:85], 0, v[146:147]
	v_lshl_add_u64 v[146:147], v[144:145], 2, v[146:147]
	v_add_co_u32_e32 v146, vcc, 0xfffff000, v146
	s_nop 1
	v_addc_co_u32_e32 v147, vcc, -1, v147, vcc
	global_store_dwordx4 v[146:147], v[6:9], off offset:-3584 nt
	global_store_dwordx4 v[146:147], v[2:5], off offset:-3568 nt

.LBB0_360:
	s_and_b64 s[4:5], s[4:5], exec
	s_movk_i32 s1, 0xec00
	s_cselect_b32 s1, 0xfffff000, s1
	v_add_u32_e32 v163, s1, v144
	s_mov_b32 s1, 0x29a00000
	s_cselect_b32 s1, s1, 0x2a600000
	s_add_u32 s1, s14, s1
	s_addc_u32 s29, s15, 0
	s_lshl_b64 s[4:5], s[16:17], 1
	s_add_u32 s4, s1, s4
	s_addc_u32 s5, s29, s5
	v_bfe_u32 v144, v126, 16, 1
	v_lshl_add_u64 v[164:165], v[138:139], 1, s[4:5]
	v_add3_u32 v126, v126, v144, s18
	v_mad_i64_i32 v[144:145], s[4:5], s0, v163, 0
	v_lshl_add_u64 v[144:145], v[144:145], 1, v[164:165]
	global_store_short_d16_hi v[144:145], v126, off nt
	v_bfe_u32 v126, v127, 16, 1
	v_add3_u32 v146, v127, v126, s18
	v_or_b32_e32 v126, 1, v163
	v_mad_i64_i32 v[126:127], s[4:5], s0, v126, 0
	v_lshl_add_u64 v[126:127], v[126:127], 1, v[164:165]
	global_store_short_d16_hi v[126:127], v146, off nt
	v_bfe_u32 v146, v128, 16, 1
	v_add3_u32 v128, v128, v146, s18
	v_or_b32_e32 v146, 2, v163
	v_mad_i64_i32 v[146:147], s[4:5], s0, v146, 0
	v_lshl_add_u64 v[146:147], v[146:147], 1, v[164:165]
	global_store_short_d16_hi v[146:147], v128, off nt
	v_bfe_u32 v128, v129, 16, 1
	v_add3_u32 v148, v129, v128, s18
	v_or_b32_e32 v128, 3, v163
	v_mad_i64_i32 v[128:129], s[4:5], s0, v128, 0
	v_lshl_add_u64 v[128:129], v[128:129], 1, v[164:165]
	global_store_short_d16_hi v[128:129], v148, off nt
	v_or_b32_e32 v148, 4, v163
	v_bfe_u32 v149, v122, 16, 1
	v_add3_u32 v122, v122, v149, s18
	v_mad_i64_i32 v[148:149], s[4:5], s0, v148, 0
	v_lshl_add_u64 v[148:149], v[148:149], 1, v[164:165]
	global_store_short_d16_hi v[148:149], v122, off nt
	v_bfe_u32 v122, v123, 16, 1
	v_add3_u32 v150, v123, v122, s18
	v_or_b32_e32 v122, 5, v163
	v_mad_i64_i32 v[122:123], s[4:5], s0, v122, 0
	v_lshl_add_u64 v[122:123], v[122:123], 1, v[164:165]
	global_store_short_d16_hi v[122:123], v150, off nt
	v_bfe_u32 v150, v124, 16, 1
	v_add3_u32 v124, v124, v150, s18
	v_or_b32_e32 v150, 6, v163
	v_mad_i64_i32 v[150:151], s[4:5], s0, v150, 0
	v_lshl_add_u64 v[150:151], v[150:151], 1, v[164:165]
	global_store_short_d16_hi v[150:151], v124, off nt
	v_bfe_u32 v124, v125, 16, 1
	v_add3_u32 v152, v125, v124, s18
	v_or_b32_e32 v124, 7, v163
	v_mad_i64_i32 v[124:125], s[4:5], s0, v124, 0
	v_lshl_add_u64 v[124:125], v[124:125], 1, v[164:165]
	global_store_short_d16_hi v[124:125], v152, off nt
	v_or_b32_e32 v152, 0x80, v163
	v_bfe_u32 v153, v118, 16, 1
	v_add3_u32 v118, v118, v153, s18
	v_mad_i64_i32 v[152:153], s[4:5], s0, v152, 0
	v_lshl_add_u64 v[152:153], v[152:153], 1, v[164:165]
	global_store_short_d16_hi v[152:153], v118, off nt
	v_bfe_u32 v118, v119, 16, 1
	v_add3_u32 v154, v119, v118, s18
	v_or_b32_e32 v118, 0x81, v163
	v_mad_i64_i32 v[118:119], s[4:5], s0, v118, 0
	v_lshl_add_u64 v[118:119], v[118:119], 1, v[164:165]
	global_store_short_d16_hi v[118:119], v154, off nt
	v_bfe_u32 v154, v120, 16, 1
	v_add3_u32 v120, v120, v154, s18
	v_or_b32_e32 v154, 0x82, v163
	v_mad_i64_i32 v[154:155], s[4:5], s0, v154, 0
	v_lshl_add_u64 v[154:155], v[154:155], 1, v[164:165]
	global_store_short_d16_hi v[154:155], v120, off nt
	v_bfe_u32 v120, v121, 16, 1
	v_add3_u32 v156, v121, v120, s18
	v_or_b32_e32 v120, 0x83, v163
	v_mad_i64_i32 v[120:121], s[4:5], s0, v120, 0
	v_lshl_add_u64 v[120:121], v[120:121], 1, v[164:165]
	global_store_short_d16_hi v[120:121], v156, off nt
	v_or_b32_e32 v156, 0x84, v163
	v_bfe_u32 v157, v110, 16, 1
	v_add3_u32 v110, v110, v157, s18
	v_mad_i64_i32 v[156:157], s[4:5], s0, v156, 0
	v_lshl_add_u64 v[156:157], v[156:157], 1, v[164:165]
	global_store_short_d16_hi v[156:157], v110, off nt
	v_bfe_u32 v110, v111, 16, 1
	v_add3_u32 v158, v111, v110, s18
	v_or_b32_e32 v110, 0x85, v163
	v_mad_i64_i32 v[110:111], s[4:5], s0, v110, 0
	v_lshl_add_u64 v[110:111], v[110:111], 1, v[164:165]
	global_store_short_d16_hi v[110:111], v158, off nt
	v_bfe_u32 v158, v112, 16, 1
	v_add3_u32 v112, v112, v158, s18
	v_or_b32_e32 v158, 0x86, v163
	v_mad_i64_i32 v[158:159], s[4:5], s0, v158, 0
	v_lshl_add_u64 v[158:159], v[158:159], 1, v[164:165]
	global_store_short_d16_hi v[158:159], v112, off nt
	v_bfe_u32 v112, v113, 16, 1
	v_add3_u32 v166, v113, v112, s18
	v_or_b32_e32 v112, 0x87, v163
	v_mad_i64_i32 v[112:113], s[0:1], s0, v112, 0
	v_bfe_u32 v163, v114, 16, 1
	v_lshl_add_u64 v[112:113], v[112:113], 1, v[164:165]
	v_add3_u32 v114, v114, v163, s18
	global_store_short_d16_hi v[112:113], v166, off nt
	global_store_short_d16_hi v[144:145], v114, off offset:32 nt
	v_bfe_u32 v114, v115, 16, 1
	v_add3_u32 v114, v115, v114, s18
	global_store_short_d16_hi v[126:127], v114, off offset:32 nt
	v_bfe_u32 v114, v116, 16, 1
	v_add3_u32 v114, v116, v114, s18
	global_store_short_d16_hi v[146:147], v114, off offset:32 nt
	v_bfe_u32 v114, v117, 16, 1
	v_add3_u32 v114, v117, v114, s18
	global_store_short_d16_hi v[128:129], v114, off offset:32 nt
	v_bfe_u32 v114, v106, 16, 1
	v_add3_u32 v106, v106, v114, s18
	global_store_short_d16_hi v[148:149], v106, off offset:32 nt
	v_bfe_u32 v106, v107, 16, 1
	v_add3_u32 v106, v107, v106, s18
	global_store_short_d16_hi v[122:123], v106, off offset:32 nt
	v_bfe_u32 v106, v108, 16, 1
	v_add3_u32 v106, v108, v106, s18
	global_store_short_d16_hi v[150:151], v106, off offset:32 nt
	v_bfe_u32 v106, v109, 16, 1
	v_add3_u32 v106, v109, v106, s18
	global_store_short_d16_hi v[124:125], v106, off offset:32 nt
	v_bfe_u32 v106, v98, 16, 1
	v_add3_u32 v98, v98, v106, s18
	global_store_short_d16_hi v[152:153], v98, off offset:32 nt
	v_bfe_u32 v98, v99, 16, 1
	v_add3_u32 v98, v99, v98, s18
	global_store_short_d16_hi v[118:119], v98, off offset:32 nt
	v_bfe_u32 v98, v100, 16, 1
	v_add3_u32 v98, v100, v98, s18
	global_store_short_d16_hi v[154:155], v98, off offset:32 nt
	v_bfe_u32 v98, v101, 16, 1
	v_add3_u32 v98, v101, v98, s18
	global_store_short_d16_hi v[120:121], v98, off offset:32 nt
	v_bfe_u32 v98, v90, 16, 1
	v_add3_u32 v90, v90, v98, s18
	global_store_short_d16_hi v[156:157], v90, off offset:32 nt
	v_bfe_u32 v90, v91, 16, 1
	v_add3_u32 v90, v91, v90, s18
	global_store_short_d16_hi v[110:111], v90, off offset:32 nt
	v_bfe_u32 v90, v92, 16, 1
	v_add3_u32 v90, v92, v90, s18
	global_store_short_d16_hi v[158:159], v90, off offset:32 nt
	v_bfe_u32 v90, v93, 16, 1
	v_add3_u32 v90, v93, v90, s18
	global_store_short_d16_hi v[112:113], v90, off offset:32 nt
	v_bfe_u32 v90, v102, 16, 1
	v_add3_u32 v90, v102, v90, s18
	global_store_short_d16_hi v[144:145], v90, off offset:64 nt
	v_bfe_u32 v90, v103, 16, 1
	v_add3_u32 v90, v103, v90, s18
	global_store_short_d16_hi v[126:127], v90, off offset:64 nt
	v_bfe_u32 v90, v104, 16, 1
	v_add3_u32 v90, v104, v90, s18
	global_store_short_d16_hi v[146:147], v90, off offset:64 nt
	v_bfe_u32 v90, v105, 16, 1
	v_add3_u32 v90, v105, v90, s18
	global_store_short_d16_hi v[128:129], v90, off offset:64 nt
	v_bfe_u32 v90, v94, 16, 1
	v_add3_u32 v90, v94, v90, s18
	global_store_short_d16_hi v[148:149], v90, off offset:64 nt
	v_bfe_u32 v90, v95, 16, 1
	v_add3_u32 v90, v95, v90, s18
	global_store_short_d16_hi v[122:123], v90, off offset:64 nt
	v_bfe_u32 v90, v96, 16, 1
	v_add3_u32 v90, v96, v90, s18
	global_store_short_d16_hi v[150:151], v90, off offset:64 nt
	v_bfe_u32 v90, v97, 16, 1
	v_add3_u32 v90, v97, v90, s18
	global_store_short_d16_hi v[124:125], v90, off offset:64 nt
	v_bfe_u32 v90, v82, 16, 1
	v_add3_u32 v82, v82, v90, s18
	global_store_short_d16_hi v[152:153], v82, off offset:64 nt
	v_bfe_u32 v82, v83, 16, 1
	v_add3_u32 v82, v83, v82, s18
	global_store_short_d16_hi v[118:119], v82, off offset:64 nt
	v_bfe_u32 v82, v84, 16, 1
	v_add3_u32 v82, v84, v82, s18
	global_store_short_d16_hi v[154:155], v82, off offset:64 nt
	v_bfe_u32 v82, v85, 16, 1
	v_add3_u32 v82, v85, v82, s18
	global_store_short_d16_hi v[120:121], v82, off offset:64 nt
	v_bfe_u32 v82, v74, 16, 1
	v_add3_u32 v74, v74, v82, s18
	global_store_short_d16_hi v[156:157], v74, off offset:64 nt
	v_bfe_u32 v74, v75, 16, 1
	v_add3_u32 v74, v75, v74, s18
	global_store_short_d16_hi v[110:111], v74, off offset:64 nt
	v_bfe_u32 v74, v76, 16, 1
	v_add3_u32 v74, v76, v74, s18
	global_store_short_d16_hi v[158:159], v74, off offset:64 nt
	v_bfe_u32 v74, v77, 16, 1
	v_add3_u32 v74, v77, v74, s18
	global_store_short_d16_hi v[112:113], v74, off offset:64 nt
	v_bfe_u32 v74, v86, 16, 1
	v_add3_u32 v74, v86, v74, s18
	global_store_short_d16_hi v[144:145], v74, off offset:96 nt
	v_bfe_u32 v74, v87, 16, 1
	v_add3_u32 v74, v87, v74, s18
	global_store_short_d16_hi v[126:127], v74, off offset:96 nt
	v_bfe_u32 v74, v88, 16, 1
	v_add3_u32 v74, v88, v74, s18
	global_store_short_d16_hi v[146:147], v74, off offset:96 nt
	v_bfe_u32 v74, v89, 16, 1
	v_add3_u32 v74, v89, v74, s18
	global_store_short_d16_hi v[128:129], v74, off offset:96 nt
	v_bfe_u32 v74, v78, 16, 1
	v_add3_u32 v74, v78, v74, s18
	global_store_short_d16_hi v[148:149], v74, off offset:96 nt
	v_bfe_u32 v74, v79, 16, 1
	v_add3_u32 v74, v79, v74, s18
	global_store_short_d16_hi v[122:123], v74, off offset:96 nt
	v_bfe_u32 v74, v80, 16, 1
	v_add3_u32 v74, v80, v74, s18
	global_store_short_d16_hi v[150:151], v74, off offset:96 nt
	v_bfe_u32 v74, v81, 16, 1
	v_add3_u32 v74, v81, v74, s18
	global_store_short_d16_hi v[124:125], v74, off offset:96 nt
	v_bfe_u32 v74, v70, 16, 1
	v_add3_u32 v70, v70, v74, s18
	global_store_short_d16_hi v[152:153], v70, off offset:96 nt
	v_bfe_u32 v70, v71, 16, 1
	v_add3_u32 v70, v71, v70, s18
	global_store_short_d16_hi v[118:119], v70, off offset:96 nt
	v_bfe_u32 v70, v72, 16, 1
	v_add3_u32 v70, v72, v70, s18
	global_store_short_d16_hi v[154:155], v70, off offset:96 nt
	v_bfe_u32 v70, v73, 16, 1
	v_add3_u32 v70, v73, v70, s18
	global_store_short_d16_hi v[120:121], v70, off offset:96 nt
	v_bfe_u32 v70, v66, 16, 1
	v_add3_u32 v66, v66, v70, s18
	global_store_short_d16_hi v[156:157], v66, off offset:96 nt
	v_bfe_u32 v66, v67, 16, 1
	v_add3_u32 v66, v67, v66, s18
	global_store_short_d16_hi v[110:111], v66, off offset:96 nt
	v_bfe_u32 v66, v68, 16, 1
	v_add3_u32 v66, v68, v66, s18
	global_store_short_d16_hi v[158:159], v66, off offset:96 nt
	v_bfe_u32 v66, v69, 16, 1
	v_add3_u32 v66, v69, v66, s18
	global_store_short_d16_hi v[112:113], v66, off offset:96 nt
	v_bfe_u32 v66, v62, 16, 1
	v_add3_u32 v62, v62, v66, s18
	global_store_short_d16_hi v[144:145], v62, off offset:256 nt
	v_bfe_u32 v62, v63, 16, 1
	v_add3_u32 v62, v63, v62, s18
	global_store_short_d16_hi v[126:127], v62, off offset:256 nt
	v_bfe_u32 v62, v64, 16, 1
	v_add3_u32 v62, v64, v62, s18
	global_store_short_d16_hi v[146:147], v62, off offset:256 nt
	v_bfe_u32 v62, v65, 16, 1
	v_add3_u32 v62, v65, v62, s18
	global_store_short_d16_hi v[128:129], v62, off offset:256 nt
	v_bfe_u32 v62, v58, 16, 1
	v_add3_u32 v58, v58, v62, s18
	global_store_short_d16_hi v[148:149], v58, off offset:256 nt
	v_bfe_u32 v58, v59, 16, 1
	v_add3_u32 v58, v59, v58, s18
	global_store_short_d16_hi v[122:123], v58, off offset:256 nt
	v_bfe_u32 v58, v60, 16, 1
	v_add3_u32 v58, v60, v58, s18
	global_store_short_d16_hi v[150:151], v58, off offset:256 nt
	v_bfe_u32 v58, v61, 16, 1
	v_add3_u32 v58, v61, v58, s18
	global_store_short_d16_hi v[124:125], v58, off offset:256 nt
	v_bfe_u32 v58, v50, 16, 1
	v_add3_u32 v50, v50, v58, s18
	global_store_short_d16_hi v[152:153], v50, off offset:256 nt
	v_bfe_u32 v50, v51, 16, 1
	v_add3_u32 v50, v51, v50, s18
	global_store_short_d16_hi v[118:119], v50, off offset:256 nt
	v_bfe_u32 v50, v52, 16, 1
	v_add3_u32 v50, v52, v50, s18
	global_store_short_d16_hi v[154:155], v50, off offset:256 nt
	v_bfe_u32 v50, v53, 16, 1
	v_add3_u32 v50, v53, v50, s18
	global_store_short_d16_hi v[120:121], v50, off offset:256 nt
	v_bfe_u32 v50, v42, 16, 1
	v_add3_u32 v42, v42, v50, s18
	global_store_short_d16_hi v[156:157], v42, off offset:256 nt
	v_bfe_u32 v42, v43, 16, 1
	v_add3_u32 v42, v43, v42, s18
	global_store_short_d16_hi v[110:111], v42, off offset:256 nt
	v_bfe_u32 v42, v44, 16, 1
	v_add3_u32 v42, v44, v42, s18
	global_store_short_d16_hi v[158:159], v42, off offset:256 nt
	v_bfe_u32 v42, v45, 16, 1
	v_add3_u32 v42, v45, v42, s18
	global_store_short_d16_hi v[112:113], v42, off offset:256 nt
	v_bfe_u32 v42, v54, 16, 1
	v_add3_u32 v42, v54, v42, s18
	global_store_short_d16_hi v[144:145], v42, off offset:288 nt
	v_bfe_u32 v42, v55, 16, 1
	v_add3_u32 v42, v55, v42, s18
	global_store_short_d16_hi v[126:127], v42, off offset:288 nt
	v_bfe_u32 v42, v56, 16, 1
	v_add3_u32 v42, v56, v42, s18
	global_store_short_d16_hi v[146:147], v42, off offset:288 nt
	v_bfe_u32 v42, v57, 16, 1
	v_add3_u32 v42, v57, v42, s18
	global_store_short_d16_hi v[128:129], v42, off offset:288 nt
	v_bfe_u32 v42, v46, 16, 1
	v_add3_u32 v42, v46, v42, s18
	global_store_short_d16_hi v[148:149], v42, off offset:288 nt
	v_bfe_u32 v42, v47, 16, 1
	v_add3_u32 v42, v47, v42, s18
	global_store_short_d16_hi v[122:123], v42, off offset:288 nt
	v_bfe_u32 v42, v48, 16, 1
	v_add3_u32 v42, v48, v42, s18
	global_store_short_d16_hi v[150:151], v42, off offset:288 nt
	v_bfe_u32 v42, v49, 16, 1
	v_add3_u32 v42, v49, v42, s18
	global_store_short_d16_hi v[124:125], v42, off offset:288 nt
	v_bfe_u32 v42, v34, 16, 1
	v_add3_u32 v34, v34, v42, s18
	global_store_short_d16_hi v[152:153], v34, off offset:288 nt
	v_bfe_u32 v34, v35, 16, 1
	v_add3_u32 v34, v35, v34, s18
	global_store_short_d16_hi v[118:119], v34, off offset:288 nt
	v_bfe_u32 v34, v36, 16, 1
	v_add3_u32 v34, v36, v34, s18
	global_store_short_d16_hi v[154:155], v34, off offset:288 nt
	v_bfe_u32 v34, v37, 16, 1
	v_add3_u32 v34, v37, v34, s18
	global_store_short_d16_hi v[120:121], v34, off offset:288 nt
	v_bfe_u32 v34, v26, 16, 1
	v_add3_u32 v26, v26, v34, s18
	global_store_short_d16_hi v[156:157], v26, off offset:288 nt
	v_bfe_u32 v26, v27, 16, 1
	v_add3_u32 v26, v27, v26, s18
	global_store_short_d16_hi v[110:111], v26, off offset:288 nt
	v_bfe_u32 v26, v28, 16, 1
	v_add3_u32 v26, v28, v26, s18
	global_store_short_d16_hi v[158:159], v26, off offset:288 nt
	v_bfe_u32 v26, v29, 16, 1
	v_add3_u32 v26, v29, v26, s18
	global_store_short_d16_hi v[112:113], v26, off offset:288 nt
	v_bfe_u32 v26, v38, 16, 1
	v_add3_u32 v26, v38, v26, s18
	global_store_short_d16_hi v[144:145], v26, off offset:320 nt
	v_bfe_u32 v26, v39, 16, 1
	v_add3_u32 v26, v39, v26, s18
	global_store_short_d16_hi v[126:127], v26, off offset:320 nt
	v_bfe_u32 v26, v40, 16, 1
	v_add3_u32 v26, v40, v26, s18
	global_store_short_d16_hi v[146:147], v26, off offset:320 nt
	v_bfe_u32 v26, v41, 16, 1
	v_add3_u32 v26, v41, v26, s18
	global_store_short_d16_hi v[128:129], v26, off offset:320 nt
	v_bfe_u32 v26, v30, 16, 1
	v_add3_u32 v26, v30, v26, s18
	global_store_short_d16_hi v[148:149], v26, off offset:320 nt
	v_bfe_u32 v26, v31, 16, 1
	v_add3_u32 v26, v31, v26, s18
	global_store_short_d16_hi v[122:123], v26, off offset:320 nt
	v_bfe_u32 v26, v32, 16, 1
	v_add3_u32 v26, v32, v26, s18
	global_store_short_d16_hi v[150:151], v26, off offset:320 nt
	v_bfe_u32 v26, v33, 16, 1
	v_add3_u32 v26, v33, v26, s18
	global_store_short_d16_hi v[124:125], v26, off offset:320 nt
	v_bfe_u32 v26, v18, 16, 1
	v_add3_u32 v18, v18, v26, s18
	global_store_short_d16_hi v[152:153], v18, off offset:320 nt
	v_bfe_u32 v18, v19, 16, 1
	v_add3_u32 v18, v19, v18, s18
	global_store_short_d16_hi v[118:119], v18, off offset:320 nt
	v_bfe_u32 v18, v20, 16, 1
	v_add3_u32 v18, v20, v18, s18
	global_store_short_d16_hi v[154:155], v18, off offset:320 nt
	v_bfe_u32 v18, v21, 16, 1
	v_add3_u32 v18, v21, v18, s18
	global_store_short_d16_hi v[120:121], v18, off offset:320 nt
	v_bfe_u32 v18, v10, 16, 1
	v_add3_u32 v10, v10, v18, s18
	global_store_short_d16_hi v[156:157], v10, off offset:320 nt
	v_bfe_u32 v10, v11, 16, 1
	v_add3_u32 v10, v11, v10, s18
	global_store_short_d16_hi v[110:111], v10, off offset:320 nt
	v_bfe_u32 v10, v12, 16, 1
	v_add3_u32 v10, v12, v10, s18
	global_store_short_d16_hi v[158:159], v10, off offset:320 nt
	v_bfe_u32 v10, v13, 16, 1
	v_add3_u32 v10, v13, v10, s18
	global_store_short_d16_hi v[112:113], v10, off offset:320 nt
	v_bfe_u32 v10, v22, 16, 1
	v_add3_u32 v10, v22, v10, s18
	global_store_short_d16_hi v[144:145], v10, off offset:352 nt
	v_bfe_u32 v10, v23, 16, 1
	v_add3_u32 v10, v23, v10, s18
	global_store_short_d16_hi v[126:127], v10, off offset:352 nt
	v_bfe_u32 v10, v24, 16, 1
	v_add3_u32 v10, v24, v10, s18
	global_store_short_d16_hi v[146:147], v10, off offset:352 nt
	v_bfe_u32 v10, v25, 16, 1
	v_add3_u32 v10, v25, v10, s18
	global_store_short_d16_hi v[128:129], v10, off offset:352 nt
	v_bfe_u32 v10, v14, 16, 1
	v_add3_u32 v10, v14, v10, s18
	global_store_short_d16_hi v[148:149], v10, off offset:352 nt
	v_bfe_u32 v10, v15, 16, 1
	v_add3_u32 v10, v15, v10, s18
	global_store_short_d16_hi v[122:123], v10, off offset:352 nt
	v_bfe_u32 v10, v16, 16, 1
	v_add3_u32 v10, v16, v10, s18
	global_store_short_d16_hi v[150:151], v10, off offset:352 nt
	v_bfe_u32 v10, v17, 16, 1
	v_add3_u32 v10, v17, v10, s18
	global_store_short_d16_hi v[124:125], v10, off offset:352 nt
	v_bfe_u32 v10, v6, 16, 1
	v_add3_u32 v6, v6, v10, s18
	global_store_short_d16_hi v[152:153], v6, off offset:352 nt
	v_bfe_u32 v6, v7, 16, 1
	v_add3_u32 v6, v7, v6, s18
	global_store_short_d16_hi v[118:119], v6, off offset:352 nt
	v_bfe_u32 v6, v8, 16, 1
	v_add3_u32 v6, v8, v6, s18
	global_store_short_d16_hi v[154:155], v6, off offset:352 nt
	v_bfe_u32 v6, v9, 16, 1
	v_add3_u32 v6, v9, v6, s18
	global_store_short_d16_hi v[120:121], v6, off offset:352 nt
	v_bfe_u32 v6, v2, 16, 1
	v_add3_u32 v2, v2, v6, s18
	global_store_short_d16_hi v[156:157], v2, off offset:352 nt
	v_bfe_u32 v2, v3, 16, 1
	v_add3_u32 v2, v3, v2, s18
	global_store_short_d16_hi v[110:111], v2, off offset:352 nt
	v_bfe_u32 v2, v4, 16, 1
	v_add3_u32 v2, v4, v2, s18
	global_store_short_d16_hi v[158:159], v2, off offset:352 nt
	v_bfe_u32 v2, v5, 16, 1
	v_add3_u32 v2, v5, v2, s18
	global_store_short_d16_hi v[112:113], v2, off offset:352 nt
	s_andn2_b64 vcc, exec, s[38:39]
	s_mov_b64 s[0:1], -1
	s_cbranch_vccnz .LBB0_308
